# q=4 prep phase: redundant clamped last-round items skipped, and the partial last rounds of prepkv / ml1 / pool rotated onto different workgroups
# speedup vs baseline: 1.0102x; 1.0014x over previous
; DI int otid() { int t = threadIdx.x & 255; asm volatile("" : "+v"(t)); return t; }
; DI void prepkv_item(const Params& p, int layer, int item, char* smem) {
;     const int hsel = item % 6, kt = (item / 6) % NCH, b = item / (6 * NCH);
;     const int tid = otid(), key = tid >> 2, sub = tid & 3;
;     const size_t row0 = seq_row(b, kt);
;     const bf16_t* prow = p.ACT + (row0 + key) * PW;
;     const bool lat = kt >= 4;
;     const int t = (kt - 4) * 64 + key;
; DI void run_phase(int ph, char* smem) {
;     ...
;         for (int k = 0; k < (n1 + G - 1) / G; ++k) { int it = bid + k * G; if (it >= n1) it = n1 - 1; prepkv_item(p, l, it, smh); }
.LBB0_205:
	s_cmpk_gt_i32 s18, 0x18bf
	s_cbranch_scc1 .LBB0_223
	s_mov_b32 s7, s18
	s_mul_hi_i32 s12, s7, 0x2aaaaaab
	s_lshr_b32 s0, s12, 31
	s_add_i32 s12, s12, s0
	s_mul_hi_i32 s0, s12, 0x3e0f83e1
	s_lshr_b32 s1, s0, 31
	s_ashr_i32 s0, s0, 5
	s_add_i32 s0, s0, s1
	s_mulk_i32 s0, 0x84
	s_sub_i32 s19, s12, s0
	s_mul_hi_i32 s0, s7, 0xa57eb503
	s_add_i32 s0, s0, s7
	s_lshr_b32 s1, s0, 31
	s_ashr_i32 s0, s0, 9
	s_add_i32 s8, s0, s1
	s_waitcnt vmcnt(28)
	v_mov_b32_e32 v48, v228
	s_cmp_gt_i32 s19, 3
	s_mov_b64 s[10:11], -1
	s_cbranch_scc0 .LBB0_207
	s_ashr_i32 s9, s8, 31
	s_lshl_b32 s6, s19, 6
	s_lshl_b64 s[0:1], s[8:9], 13
	s_add_i32 s9, s6, 0xffffff00
	s_add_u32 s0, s0, s9
	s_addc_u32 s1, s1, 0
	s_mov_b64 s[10:11], 0

; DI int otid() { int t = threadIdx.x & 255; asm volatile("" : "+v"(t)); return t; }
; DI void ml1_item(const Params& p, int item, char* smem) {
;     ...
;     const int c = item % NCH, head = (item / NCH) & 3, b = item / (NCH * 4);
;     const int tid = otid();
;     const size_t row0 = seq_row(b, c);
; DI void run_phase(int ph, char* smem) {
;     ...
;         for (int k = 0; k < (n2 + G - 1) / G; ++k) { int it = bid + k * G; if (it >= n2) it = n2 - 1; ml1_item(p, it, smh); }
.LBB0_226:
	v_readlane_b32 s0, v253, 5
	v_readlane_b32 s1, v253, 2
	s_addk_i32 s1, 0x140
	s_cmp_ge_i32 s1, s0
	s_cselect_b32 s4, s0, 0
	s_sub_i32 s1, s1, s4
	s_mul_i32 s0, s13, s0
	s_add_i32 s0, s0, s1
	s_cmpk_gt_i32 s0, 0x107f
	s_cbranch_scc1 .LBB0_240
	s_mul_hi_i32 s1, s0, 0x3e0f83e1
	s_ashr_i32 s18, s1, 5
	s_lshr_b32 s4, s1, 31
	s_add_i32 s18, s18, s4
	s_mul_i32 s5, s18, 0x84
	s_sub_i32 s17, s0, s5
	s_ashr_i32 s0, s1, 7
	s_add_i32 s6, s0, s4
	s_cmp_lt_i32 s17, 4
	s_waitcnt vmcnt(22)
	v_mov_b32_e32 v34, v228
	s_cselect_b64 s[4:5], -1, 0
	s_cmp_gt_i32 s17, 3
	s_mov_b64 s[8:9], -1
	s_cbranch_scc0 .LBB0_228
	s_ashr_i32 s7, s6, 31
	s_lshl_b64 s[0:1], s[6:7], 13
	s_lshl_b32 s7, s17, 6
	s_addk_i32 s7, 0xff00
	s_add_u32 s0, s0, s7
	s_addc_u32 s1, s1, 0
	s_mov_b64 s[8:9], 0

; DI void run_phase(int ph, char* smem) {
;     ...
;         const int npl = NB * 128 * 4, npc = last ? 0 : NB * 4 * 4, n3 = npl + npc;
;         for (int k = 0; k < (n3 + G - 1) / G; ++k) {
;             int it = bid + k * G; if (it >= n3) it = n3 - 1;
.LBB0_240:
	v_readlane_b32 s0, v254, 4
	v_readlane_b32 s1, v254, 5
	s_and_b64 s[0:1], s[0:1], exec
	s_movk_i32 s0, 0xfff
	s_cselect_b32 s10, s0, 0x107f
	v_readlane_b32 s2, v253, 5
	s_add_i32 s0, s2, s10
	s_ashr_i32 s1, s0, 31
	s_abs_i32 s0, s0
	s_mul_hi_u32 s4, s0, s16
	s_mul_i32 s5, s4, s14
	s_sub_i32 s0, s0, s5
	s_xor_b32 s1, s1, s15
	s_add_i32 s5, s4, 1
	s_sub_i32 s6, s0, s14
	s_cmp_ge_u32 s0, s14
	s_cselect_b32 s4, s5, s4
	s_cselect_b32 s0, s6, s0
	s_add_i32 s5, s4, 1
	s_cmp_ge_u32 s0, s14
	s_cselect_b32 s0, s5, s4
	s_xor_b32 s0, s0, s1
	s_sub_i32 s11, s0, s1
	s_cmp_lt_i32 s11, 1
	s_cbranch_scc1 .LBB0_311
	v_readlane_b32 s14, v254, 7
	v_readlane_b32 s44, v253, 22
	v_readlane_b32 s15, v254, 8
	v_readlane_b32 s45, v253, 23
	s_lshl_b64 s[0:1], s[14:15], 16
	v_readlane_b32 s46, v253, 24
	v_readlane_b32 s47, v253, 25
	v_readlane_b32 s48, v253, 26
	v_readlane_b32 s49, v253, 27
	v_readlane_b32 s52, v253, 30
	v_readlane_b32 s53, v253, 31
	v_readlane_b32 s54, v253, 32
	v_readlane_b32 s55, v253, 33
	v_readlane_b32 s56, v253, 34
	v_readlane_b32 s57, v253, 35
	v_readlane_b32 s58, v253, 36
	v_readlane_b32 s59, v253, 37
	s_mov_b64 s[4:5], s[44:45]
	v_readlane_b32 s52, v253, 49
	s_add_u32 s12, s4, s0
	v_readlane_b32 s53, v253, 50
	v_readlane_b32 s54, v253, 51
	v_readlane_b32 s55, v253, 52
	v_readlane_b32 s56, v253, 53
	v_readlane_b32 s57, v253, 54
	v_readlane_b32 s58, v253, 55
	v_readlane_b32 s59, v253, 56
	v_readlane_b32 s60, v253, 57
	v_readlane_b32 s61, v253, 58
	v_readlane_b32 s62, v253, 59
	v_readlane_b32 s63, v253, 60
	v_readlane_b32 s64, v253, 61
	v_readlane_b32 s65, v253, 62
	s_addc_u32 s13, s5, s1
	s_lshl_b32 s14, s14, 8
	s_add_i32 s15, s25, 0x800
	s_add_i32 s16, s25, 0x5000
	s_add_i32 s17, s25, 0x9400
	s_mov_b32 s18, 0
	v_readlane_b32 s19, v253, 2
	s_addk_i32 s19, 0xc0
	s_cmp_ge_i32 s19, s2
	s_cselect_b32 s50, s2, 0
	s_sub_i32 s19, s19, s50
	v_readlane_b32 s50, v253, 28
	v_readlane_b32 s51, v253, 29
	s_mov_b64 s[6:7], s[46:47]
	s_mov_b64 s[8:9], s[48:49]
	v_readlane_b32 s66, v253, 63
	v_readlane_b32 s67, v254, 0
	s_branch .LBB0_243

; DI void pool_item(const Params& p, int layer, int seq, int tile, int g, char* smem) {
;     ...
;     {
;         u32x4 uch[3]; float wv[16];
;         const float* pw = p.pool_w + ((size_t)layer * 4 + g) * 4096;
; #pragma unroll
;         for (int i = 0; i < 3; ++i) {
;             const int c = tid + THREADS * i, rr = c >> 3, c8 = (c & 7) * 8, t = t0 - 8 + rr;
;             uch[i] = (u32x4){0u, 0u, 0u, 0u};
;             if (c < 640 && t >= 0 && t < Ls) uch[i] = *(const u32x4*)(p.ACT + (rbase + t) * PW + 768 + g * 64 + c8);
; DI void run_phase(int ph, char* smem) {
;     ...
;         for (int k = 0; k < (n3 + G - 1) / G; ++k) {
;             int it = bid + k * G; if (it >= n3) it = n3 - 1;
;             if (it < npl) pool_item(p, l, it >> 9, (it >> 2) & 127, it & 3, smh);
;             else { const int i2 = it - npl; pool_item(p, l, 8 + (i2 >> 4), (i2 >> 2) & 3, i2 & 3, smh); }
.LBB0_243:
	s_min_i32 s0, s10, s19
	s_lshr_b32 s22, s0, 2
	s_mul_i32 s0, s18, s2
	v_readlane_b32 s1, v253, 2
	s_addk_i32 s1, 0xc0
	s_cmp_ge_i32 s1, s2
	s_cselect_b32 s20, s2, 0
	s_sub_i32 s1, s1, s20
	s_add_i32 s0, s0, s1
	s_cmp_gt_i32 s0, s10
	s_cbranch_scc1 .LBB0_311
	s_and_b32 s21, s0, 3
	s_lshl_b32 s20, s0, 4
	s_cmpk_gt_i32 s0, 0xfff
	s_mov_b64 s[0:1], -1
	s_cbranch_scc0 .LBB0_275
	v_mov_b32_e32 v12, v228
	s_and_b32 s27, s20, 0xc0
	s_add_i32 s8, s27, -8
	v_ashrrev_i32_e32 v0, 3, v12
	v_lshlrev_b32_e32 v17, 3, v12
	v_add_u32_e32 v1, s8, v0
	s_movk_i32 s0, 0x280
	s_movk_i32 s4, 0x100
	s_and_b32 s26, s20, 0x700
	v_and_b32_e32 v16, 56, v17
	v_cmp_gt_i32_e64 s[0:1], s0, v12
	v_cmp_gt_u32_e32 vcc, s4, v1
	s_bitset1_b32 s26, 16
	s_lshl_b32 s23, s21, 6
	s_and_b64 s[6:7], s[0:1], vcc
	v_mov_b32_e32 v0, 0
	v_lshlrev_b32_e32 v14, 1, v16
	v_mov_b32_e32 v4, 0
	v_mov_b32_e32 v5, 0
	v_mov_b32_e32 v6, 0
	v_mov_b32_e32 v7, 0
	s_and_saveexec_b64 s[4:5], s[6:7]
	s_cbranch_execz .LBB0_246
	v_or_b32_e32 v1, s26, v1
	s_movk_i32 s2, 0x1400
	v_mul_lo_u32 v160, v1, s2
	v_lshl_add_u64 v[2:3], s[64:65], 0, v[160:161]
	s_lshl_b32 s74, s23, 1
	v_lshl_add_u64 v[2:3], v[2:3], 0, s[74:75]
	v_mov_b32_e32 v15, v161
	v_lshl_add_u64 v[2:3], v[2:3], 0, v[14:15]
	global_load_dwordx4 v[4:7], v[2:3], off offset:1536
